# combined: one barrier event per period with static priorities in the three GEMM mainloops, attention K/V two-tile prefetch, EpiResLn statistics loads issued together, x->f16 loop with 16 loads in flig
# baseline (speedup 1.0000x reference)
; #define PG8_LAS __attribute__((address_space(3)))
;     __device__ __forceinline__ void operator()(f32x4 (&acc)[2][2][4][2], const Unit& u, int wr, int wc, int fr, int fq) const {
;     ...
;         if (t < 256) { const size_t row = (size_t)u.pm * BM + t;
;             float s = 0.f, q = 0.f;
; #pragma unroll
;             for (int k4 = 0; k4 < 4; ++k4) { const unsigned long long w = __hip_atomic_load((const unsigned long long*)(st + row * 8 + 2 * k4), __ATOMIC_RELAXED, __HIP_MEMORY_SCOPE_AGENT);
;                 s += __uint_as_float((unsigned)w); q += __uint_as_float((unsigned)(w >> 32)); }
;             const float mean = s * (1.f / 1024.f), rstd = 1.f / sqrtf(q * (1.f / 1024.f) - mean * mean + eps);
;             *(PG8_LAS f32x2s*)(sl + 2 * t) = (f32x2s){mean, rstd}; }
.LBB0_375:
	s_or_b64 exec, exec, s[28:29]
	s_barrier
	s_and_saveexec_b64 s[28:29], s[4:5]
	s_cbranch_execz .LBB0_377
	s_lshl_b64 s[4:5], s[26:27], 13
	s_add_u32 s4, s54, s4
	s_addc_u32 s5, s72, s5
	s_waitcnt lgkmcnt(0)
	v_lshlrev_b64 v[2:3], 5, v[0:1]
	v_lshl_add_u64 v[2:3], s[4:5], 0, v[2:3]
	global_load_dwordx2 v[4:5], v[2:3], off sc1
	global_load_dwordx2 v[6:7], v[2:3], off offset:8 sc1
	global_load_dwordx2 v[246:247], v[2:3], off offset:16 sc1
	global_load_dwordx2 v[2:3], v[2:3], off offset:24 sc1
	s_mov_b32 s4, 0x3a800000
	v_lshl_add_u32 v0, v0, 3, 0
	v_add_u32_e32 v0, 0x20000, v0
	s_waitcnt vmcnt(0)
	v_add_f32_e32 v1, 0, v4
	v_add_f32_e32 v4, 0, v5
	v_add_f32_e32 v1, v1, v6
	v_add_f32_e32 v4, v4, v7
	v_add_f32_e32 v1, v1, v246
	v_add_f32_e32 v4, v4, v247
	v_add_f32_e32 v1, v1, v2
	v_mul_f32_e32 v2, 0x3a800000, v1
	v_add_f32_e32 v3, v4, v3
	v_mul_f32_e32 v1, v2, v2
	v_fma_f32 v1, v3, s4, -v1
	v_add_f32_e32 v1, 0x3727c5ac, v1
	s_mov_b32 s4, 0xf800000
	v_cmp_gt_f32_e32 vcc, s4, v1
	v_mul_f32_e32 v3, 0x4f800000, v1
	s_nop 0
	v_cndmask_b32_e32 v1, v1, v3, vcc
	v_sqrt_f32_e32 v3, v1
	s_nop 0
	v_add_u32_e32 v4, -1, v3
	v_fma_f32 v5, -v4, v3, v1
	v_cmp_ge_f32_e64 s[4:5], 0, v5
	v_add_u32_e32 v5, 1, v3
	s_nop 0
	v_cndmask_b32_e64 v4, v3, v4, s[4:5]
	v_fma_f32 v3, -v5, v3, v1
	v_cmp_lt_f32_e64 s[4:5], 0, v3
	s_nop 1
	v_cndmask_b32_e64 v3, v4, v5, s[4:5]
	v_mul_f32_e32 v4, 0x37800000, v3
	v_cndmask_b32_e32 v3, v3, v4, vcc
	v_cmp_class_f32_e32 vcc, v1, v203
	s_nop 1
	v_cndmask_b32_e32 v1, v3, v1, vcc
	v_div_scale_f32 v3, s[4:5], v1, v1, 1.0
	v_rcp_f32_e32 v4, v3
	s_nop 0
	v_fma_f32 v5, -v3, v4, 1.0
	v_fmac_f32_e32 v4, v5, v4
	v_div_scale_f32 v5, vcc, 1.0, v1, 1.0
	v_mul_f32_e32 v6, v5, v4
	v_fma_f32 v7, -v3, v6, v5
	v_fmac_f32_e32 v6, v7, v4
	v_fma_f32 v3, -v3, v6, v5
	v_div_fmas_f32 v3, v3, v4, v6
	v_div_fixup_f32 v3, v3, v1, 1.0
	ds_write_b64 v0, v[2:3]

; __global__ void __launch_bounds__(512, 2) fwd_kernel(Args args) {
	.amdhsa_kernel _Z10fwd_kernel4Args
		.amdhsa_group_segment_fixed_size 0
		.amdhsa_private_segment_fixed_size 0
		.amdhsa_kernarg_size 408
		.amdhsa_user_sgpr_count 2
		.amdhsa_user_sgpr_dispatch_ptr 0
		.amdhsa_user_sgpr_queue_ptr 0
		.amdhsa_user_sgpr_kernarg_segment_ptr 1
		.amdhsa_user_sgpr_dispatch_id 0
		.amdhsa_user_sgpr_kernarg_preload_length 0
		.amdhsa_user_sgpr_kernarg_preload_offset 0
		.amdhsa_user_sgpr_private_segment_size 0
		.amdhsa_uses_dynamic_stack 0
		.amdhsa_enable_private_segment 0
		.amdhsa_system_sgpr_workgroup_id_x 1
		.amdhsa_system_sgpr_workgroup_id_y 0
		.amdhsa_system_sgpr_workgroup_id_z 0
		.amdhsa_system_sgpr_workgroup_info 0
		.amdhsa_system_vgpr_workitem_id 2
		.amdhsa_next_free_vgpr 248
		.amdhsa_next_free_sgpr 100
		.amdhsa_accum_offset 248
		.amdhsa_reserve_vcc 1
		.amdhsa_float_round_mode_32 0
		.amdhsa_float_round_mode_16_64 0
		.amdhsa_float_denorm_mode_32 3
		.amdhsa_float_denorm_mode_16_64 3
		.amdhsa_dx10_clamp 1
		.amdhsa_ieee_mode 1
		.amdhsa_fp16_overflow 0
		.amdhsa_tg_split 0
		.amdhsa_exception_fp_ieee_invalid_op 0
		.amdhsa_exception_fp_denorm_src 0
		.amdhsa_exception_fp_ieee_div_zero 0
		.amdhsa_exception_fp_ieee_overflow 0
		.amdhsa_exception_fp_ieee_underflow 0
		.amdhsa_exception_fp_ieee_inexact 0
		.amdhsa_exception_int_div_zero 0
	.end_amdhsa_kernel

; __global__ void __launch_bounds__(512, 2) fwd_kernel(Args args) {
amdhsa.kernels:
  - .agpr_count:     0
    .args:
      - .offset:         0
        .size:           152
        .value_kind:     by_value
      - .offset:         152
        .size:           4
        .value_kind:     hidden_block_count_x
      - .offset:         156
        .size:           4
        .value_kind:     hidden_block_count_y
      - .offset:         160
        .size:           4
        .value_kind:     hidden_block_count_z
      - .offset:         164
        .size:           2
        .value_kind:     hidden_group_size_x
      - .offset:         166
        .size:           2
        .value_kind:     hidden_group_size_y
      - .offset:         168
        .size:           2
        .value_kind:     hidden_group_size_z
      - .offset:         170
        .size:           2
        .value_kind:     hidden_remainder_x
      - .offset:         172
        .size:           2
        .value_kind:     hidden_remainder_y
      - .offset:         174
        .size:           2
        .value_kind:     hidden_remainder_z
      - .offset:         192
        .size:           8
        .value_kind:     hidden_global_offset_x
      - .offset:         200
        .size:           8
        .value_kind:     hidden_global_offset_y
      - .offset:         208
        .size:           8
        .value_kind:     hidden_global_offset_z
      - .offset:         216
        .size:           2
        .value_kind:     hidden_grid_dims
      - .offset:         240
        .size:           8
        .value_kind:     hidden_multigrid_sync_arg
      - .offset:         272
        .size:           4
        .value_kind:     hidden_dynamic_lds_size
    .group_segment_fixed_size: 0
    .kernarg_segment_align: 8
    .kernarg_segment_size: 408
    .language:       OpenCL C
    .language_version:
      - 2
      - 0
    .max_flat_workgroup_size: 512
    .name:           _Z10fwd_kernel4Args
    .private_segment_fixed_size: 0
    .sgpr_count:     106
    .sgpr_spill_count: 143
    .symbol:         _Z10fwd_kernel4Args.kd
    .uniform_work_group_size: 1
    .uses_dynamic_stack: false
    .vgpr_count:     248
    .vgpr_spill_count: 0
    .wavefront_size: 64
